# P5 out-proj GEMM: delay odd workgroups (per-XCD index) by ~12us at phase start so residual-read epilogues overlap the other half's MFMA loops
# baseline (speedup 1.0000x reference)
; template <class Epi>
; __device__ __forceinline__ void gemm_phase(const u16* A, const u16* Bt, int K, int nN, Epi epi) {
;   {
;     int x = epi.p.vx, j = epi.p.vj;
;     int li = j;
;     int mg = li / (nN * 8), rem = li % (nN * 8);
;     int brow = (x * 32 + mg * 8 + (rem & 7)) * 256, bcol = (rem >> 3) * 256;
;     for (int rd = 0; rd < nN; ++rd) {
;       int nbrow = 0, nbcol = 0;
;       bool has_next = rd + 1 < nN;
;       if (has_next) {
;         int l2 = (rd + 1) * 32 + j;
;         int mg2 = l2 / (nN * 8), rem2 = l2 % (nN * 8);
;         nbrow = (x * 32 + mg2 * 8 + (rem2 & 7)) * 256; nbcol = (rem2 >> 3) * 256;
;       }
;       gemm_tile(A, Bt, K, brow, bcol, rd == 0, has_next, nbrow, nbcol, epi);
.LBB0_443:
	s_or_b64 exec, exec, s[0:1]
	s_add_u32 s56, s34, 0x1e000000
	s_addc_u32 s57, s35, 0
	s_ashr_i32 s0, s80, 31
	s_lshr_b32 s0, s0, 27
	s_add_i32 s0, s80, s0
	s_and_b32 s1, s0, 0xffffffe0
	s_lshr_b32 s0, s0, 2
	s_sub_i32 s1, s80, s1
	s_and_b32 s0, s0, 0x3ffffff8
	s_add_i32 s0, s0, s81
	s_and_b32 s2, s1, 7
	s_or_b32 s0, s0, s2
	s_lshl_b32 s58, s0, 8
	s_lshl_b32 s0, s1, 5
	s_and_b32 s59, s0, 0xffffff00
	s_add_u32 s6, s34, 0x16000000
	s_addc_u32 s7, s35, 0
	s_add_u32 s8, s34, 0x1f600000
	s_addc_u32 s9, s35, 0
	s_mov_b32 s1, 0
	v_mov_b32_e32 v129, 0
	s_mov_b64 s[4:5], 0x80
	s_mov_b32 s60, 0x8000
	s_movk_i32 s61, 0x3c0
	s_mov_b64 s[10:11], 0x1e000100
	s_mov_b64 s[12:13], 0x100
	s_mov_b64 s[14:15], 0x1e000180
	s_mov_b64 s[16:17], 0x180
	s_mov_b64 s[18:19], 0x780
	s_movk_i32 s62, 0x100
	v_mov_b32_e32 v160, 1
	s_mov_b32 s2, s58
	s_mov_b32 s0, s59
	s_waitcnt lgkmcnt(0)
	s_barrier
	s_bitcmp1_b32 s80, 0
	s_cbranch_scc0 .Lmy_nostag_P5
	s_sleep 127
	s_sleep 127
	s_sleep 127
.Lmy_nostag_P5:
	s_branch .LBB0_445
